# v52 + diff loops: K-fragment reads of the next half tile issued after the softmax block (land under the P.V MFMAs)
# baseline (speedup 1.0000x reference)
; #define LAS __attribute__((address_space(3)))
; DI int v_rd_base(int lane) { return ((lane & 3) << 3) | (((lane >> 2) & 3) << 6) | (((lane >> 4) & 1) << 5) | (((lane >> 5) & 1) << 8); }
; DI void pv_mma(f32x16* o, const s16x4* vf, bf16x8 pa0, bf16x8 pa1) {
;     ...
; #pragma unroll
;     for (int d0 = 0; d0 < 4; ++d0) {
;         o[d0] = __builtin_amdgcn_mfma_f32_32x32x16_bf16(pa0, ATT_PK(vf[4 * d0], vf[4 * d0 + 1]), o[d0], 0, 0, 0);
;         o[d0] = __builtin_amdgcn_mfma_f32_32x32x16_bf16(pa1, ATT_PK(vf[4 * d0 + 2], vf[4 * d0 + 3]), o[d0], 0, 0, 0); }
;     ...
; }
; template <int DQK, int D0A, int D0B> DI void k_reads(bf16x8* kf, const LAS unsigned char* Ks, int half, int r32, int hi) {
; #pragma unroll
;     for (int d0 = D0A; d0 < D0B; ++d0) kf[d0 - D0A] = *(const LAS bf16x8*)(Ks + half * (32 * DQK * 2) + kswz<DQK>(r32, (d0 * 16 + hi * 8) * 2));
; }
; template <int D0A, int D0B> DI void qk_mma(f32x16& p, const bf16x8* kf, const bf16x8* qr) {
; #pragma unroll
;     for (int d0 = D0A; d0 < D0B; ++d0) {
;         if (d0 == 0) { f32x16 z; _Pragma("unroll") for (int r = 0; r < 16; ++r) z[r] = 0.f; p = __builtin_amdgcn_mfma_f32_32x32x16_bf16(kf[0], qr[0], z, 0, 0, 0); }
;         else p = __builtin_amdgcn_mfma_f32_32x32x16_bf16(kf[d0 - D0A], qr[d0], p, 0, 0, 0); }
; }
; template <int DQK, int MODE, int LDQ, int LDK, int LDV> ...
;     ...
;     const int vbase = (int)(unsigned)(size_t)lds + V_OFF + v_rd_base(lane);
;     ...
;     constexpr int NDA = ND0 > 6 ? 6 : ND0;
.LBB0_1922:
	s_add_i32 s3, s0, -1
	s_lshl_b32 s2, s1, 14
	v_add_u32_e32 v121, s2, v106
	ds_read_b64_tr_b16 v[144:145], v121 offset:0
	ds_read_b64_tr_b16 v[146:147], v121 offset:0x800
	ds_read_b64_tr_b16 v[148:149], v121 offset:0x1000
	ds_read_b64_tr_b16 v[150:151], v121 offset:0x1800
	ds_read_b64_tr_b16 v[152:153], v121 offset:0x200
	ds_read_b64_tr_b16 v[154:155], v121 offset:0xa00
	ds_read_b64_tr_b16 v[156:157], v121 offset:0x1200
	ds_read_b64_tr_b16 v[158:159], v121 offset:0x1a00
	ds_read_b64_tr_b16 v[162:163], v121 offset:0x400
	ds_read_b64_tr_b16 v[164:165], v121 offset:0xc00
	ds_read_b64_tr_b16 v[166:167], v121 offset:0x1400
	ds_read_b64_tr_b16 v[168:169], v121 offset:0x1c00
	ds_read_b64_tr_b16 v[170:171], v121 offset:0x600
	ds_read_b64_tr_b16 v[172:173], v121 offset:0xe00
	ds_read_b64_tr_b16 v[174:175], v121 offset:0x1600
	ds_read_b64_tr_b16 v[176:177], v121 offset:0x1e00
	s_setprio 2
	v_exp_f32_e32 v64, v64
	v_exp_f32_e32 v65, v65
	v_exp_f32_e32 v66, v66
	v_exp_f32_e32 v67, v67
	v_exp_f32_e32 v68, v68
	v_exp_f32_e32 v69, v69
	v_add_f32_e32 v126, v65, v64
	v_exp_f32_e32 v70, v70
	v_add_f32_e32 v126, v66, v126
	v_exp_f32_e32 v71, v71
	v_add_f32_e32 v126, v67, v126
	v_exp_f32_e32 v72, v72
	v_add_f32_e32 v126, v68, v126
	v_exp_f32_e32 v73, v73
	v_add_f32_e32 v126, v69, v126
	v_exp_f32_e32 v74, v74
	v_add_f32_e32 v126, v70, v126
	v_exp_f32_e32 v75, v75
	v_add_f32_e32 v126, v71, v126
	v_exp_f32_e32 v76, v76
	v_add_f32_e32 v126, v72, v126
	v_exp_f32_e32 v77, v77
	v_add_f32_e32 v126, v73, v126
	v_exp_f32_e32 v78, v78
	v_add_f32_e32 v126, v74, v126
	v_exp_f32_e32 v79, v79
	v_add_f32_e32 v126, v75, v126
	v_add_f32_e32 v126, v76, v126
	v_add_f32_e32 v126, v77, v126
	v_add_f32_e32 v126, v78, v126
	v_add_f32_e32 v126, v79, v126
	v_add_f32_e32 v120, v126, v120
	v_cvt_pk_bf16_f32 v64, v64, v65
	v_cvt_pk_bf16_f32 v65, v66, v67
	v_cvt_pk_bf16_f32 v66, v68, v69
	v_cvt_pk_bf16_f32 v67, v70, v71
	v_cvt_pk_bf16_f32 v68, v72, v73
	v_cvt_pk_bf16_f32 v69, v74, v75
	v_cvt_pk_bf16_f32 v70, v76, v77
	v_cvt_pk_bf16_f32 v71, v78, v79
	s_nop 0
	v_permlane32_swap_b32_e32 v64, v66
	v_permlane32_swap_b32_e32 v65, v67
	v_permlane32_swap_b32_e32 v68, v70
	v_permlane32_swap_b32_e32 v69, v71
	s_waitcnt lgkmcnt(0)
	s_add_i32 s99, s22, 0xffffa000
	s_and_b32 s99, s99, 0x6000
	v_add_u32_e32 v196, s99, v114
	v_add_u32_e32 v197, v196, v115
	v_add_u32_e32 v198, v196, v116
	v_add_u32_e32 v199, v196, v117
	v_add_u32_e32 v196, v196, v118
	ds_read_b128 v[122:125], v197 offset:4096
	ds_read_b128 v[132:135], v198 offset:4096
	ds_read_b128 v[136:139], v199 offset:4096
	ds_read_b128 v[140:143], v196 offset:4096
	s_setprio 1
	v_mfma_f32_32x32x16_bf16 v[0:15], v[64:67], v[144:147], v[0:15]
	s_cmp_lt_i32 s3, s55
	s_cselect_b64 vcc, -1, 0
	s_cmp_ge_i32 s3, s97
	s_cselect_b64 s[74:75], -1, 0
	s_or_b64 s[74:75], vcc, s[74:75]
	s_and_b64 vcc, exec, s[74:75]
	v_mfma_f32_32x32x16_bf16 v[48:63], v[64:67], v[152:155], v[48:63]
	v_mfma_f32_32x32x16_bf16 v[32:47], v[64:67], v[162:165], v[32:47]
	v_mfma_f32_32x32x16_bf16 v[16:31], v[64:67], v[170:173], v[16:31]
	v_mfma_f32_32x32x16_bf16 v[0:15], v[68:71], v[148:151], v[0:15]
	v_mfma_f32_32x32x16_bf16 v[48:63], v[68:71], v[156:159], v[48:63]
	v_mfma_f32_32x32x16_bf16 v[32:47], v[68:71], v[166:169], v[32:47]
	v_mfma_f32_32x32x16_bf16 v[16:31], v[68:71], v[174:177], v[16:31]
	s_waitcnt lgkmcnt(0)
	v_mfma_f32_32x32x16_bf16 v[64:79], v[122:125], v[92:95], 0
	v_mfma_f32_32x32x16_bf16 v[64:79], v[132:135], v[88:91], v[64:79]
	v_mfma_f32_32x32x16_bf16 v[64:79], v[136:139], v[84:87], v[64:79]
	v_mfma_f32_32x32x16_bf16 v[64:79], v[140:143], v[80:83], v[64:79]
	s_setprio 0
	v_add_u32_e32 v122, s7, v119
	s_cbranch_vccnz .LBB0_1924
	v_add_u32_e32 v138, 0x28908, v122
	v_add_u32_e32 v140, 0x28920, v122
	v_add_u32_e32 v142, 0x28928, v122
	v_add_u32_e32 v124, 0x28940, v122
	v_add_u32_e32 v126, 0x28948, v122
	v_add_u32_e32 v132, 0x28960, v122
	v_add_u32_e32 v134, 0x28968, v122
	v_add_u32_e32 v123, 0x28900, v122
	ds_read2_b32 v[124:125], v124 offset1:1
	ds_read2_b32 v[126:127], v126 offset1:1
	ds_read2_b32 v[132:133], v132 offset1:1
	ds_read2_b32 v[134:135], v134 offset1:1
	ds_read2_b32 v[136:137], v123 offset1:1
	ds_read2_b32 v[138:139], v138 offset1:1
	ds_read2_b32 v[140:141], v140 offset1:1
	ds_read2_b32 v[142:143], v142 offset1:1
	s_waitcnt lgkmcnt(0)
	v_pk_add_f32 v[78:79], v[78:79], v[134:135]
	v_pk_add_f32 v[76:77], v[76:77], v[132:133]
	v_pk_add_f32 v[74:75], v[74:75], v[126:127]
	v_pk_add_f32 v[72:73], v[72:73], v[124:125]
	v_pk_add_f32 v[70:71], v[70:71], v[142:143]
	v_pk_add_f32 v[68:69], v[68:69], v[140:141]
	v_pk_add_f32 v[66:67], v[66:67], v[138:139]
	v_pk_add_f32 v[64:65], v[64:65], v[136:137]
; #define LAS __attribute__((address_space(3)))
; DI void pv_mma(f32x16* o, const s16x4* vf, bf16x8 pa0, bf16x8 pa1) {
;     ...
; #pragma unroll
;     for (int d0 = 0; d0 < 4; ++d0) {
;         o[d0] = __builtin_amdgcn_mfma_f32_32x32x16_bf16(pa0, ATT_PK(vf[4 * d0], vf[4 * d0 + 1]), o[d0], 0, 0, 0);
;         o[d0] = __builtin_amdgcn_mfma_f32_32x32x16_bf16(pa1, ATT_PK(vf[4 * d0 + 2], vf[4 * d0 + 3]), o[d0], 0, 0, 0); }
;     ...
; }
; template <int DQK, int D0A, int D0B> DI void k_reads(bf16x8* kf, const LAS unsigned char* Ks, int half, int r32, int hi) {
; #pragma unroll
;     for (int d0 = D0A; d0 < D0B; ++d0) kf[d0 - D0A] = *(const LAS bf16x8*)(Ks + half * (32 * DQK * 2) + kswz<DQK>(r32, (d0 * 16 + hi * 8) * 2));
; }
; template <int D0A, int D0B> DI void qk_mma(f32x16& p, const bf16x8* kf, const bf16x8* qr) {
; #pragma unroll
;     for (int d0 = D0A; d0 < D0B; ++d0) {
;         if (d0 == 0) { f32x16 z; _Pragma("unroll") for (int r = 0; r < 16; ++r) z[r] = 0.f; p = __builtin_amdgcn_mfma_f32_32x32x16_bf16(kf[0], qr[0], z, 0, 0, 0); }
;         else p = __builtin_amdgcn_mfma_f32_32x32x16_bf16(kf[d0 - D0A], qr[d0], p, 0, 0, 0); }
; }
.LBB0_1924:
	ds_read_b64_tr_b16 v[144:145], v121 offset:0x2000
	ds_read_b64_tr_b16 v[146:147], v121 offset:0x2800
	ds_read_b64_tr_b16 v[148:149], v121 offset:0x3000
	ds_read_b64_tr_b16 v[150:151], v121 offset:0x3800
	ds_read_b64_tr_b16 v[152:153], v121 offset:0x2200
	ds_read_b64_tr_b16 v[154:155], v121 offset:0x2a00
	ds_read_b64_tr_b16 v[156:157], v121 offset:0x3200
	ds_read_b64_tr_b16 v[158:159], v121 offset:0x3a00
	ds_read_b64_tr_b16 v[162:163], v121 offset:0x2400
	ds_read_b64_tr_b16 v[164:165], v121 offset:0x2c00
	ds_read_b64_tr_b16 v[166:167], v121 offset:0x3400
	ds_read_b64_tr_b16 v[168:169], v121 offset:0x3c00
	ds_read_b64_tr_b16 v[170:171], v121 offset:0x2600
	ds_read_b64_tr_b16 v[172:173], v121 offset:0x2e00
	ds_read_b64_tr_b16 v[174:175], v121 offset:0x3600
	ds_read_b64_tr_b16 v[176:177], v121 offset:0x3e00
	s_setprio 2
	v_exp_f32_e32 v64, v64
	v_exp_f32_e32 v65, v65
	v_exp_f32_e32 v66, v66
	v_exp_f32_e32 v67, v67
	v_exp_f32_e32 v68, v68
	v_exp_f32_e32 v69, v69
	v_add_f32_e32 v121, v65, v64
	v_exp_f32_e32 v70, v70
	v_add_f32_e32 v121, v66, v121
	v_exp_f32_e32 v71, v71
	v_add_f32_e32 v121, v67, v121
	v_exp_f32_e32 v72, v72
	v_add_f32_e32 v121, v68, v121
	v_exp_f32_e32 v73, v73
	v_add_f32_e32 v121, v69, v121
	v_exp_f32_e32 v74, v74
	v_add_f32_e32 v121, v70, v121
	v_exp_f32_e32 v75, v75
	v_add_f32_e32 v121, v71, v121
	v_exp_f32_e32 v76, v76
	v_add_f32_e32 v121, v72, v121
	v_exp_f32_e32 v77, v77
	v_add_f32_e32 v121, v73, v121
	v_exp_f32_e32 v78, v78
	v_add_f32_e32 v121, v74, v121
	v_exp_f32_e32 v79, v79
	v_add_f32_e32 v121, v75, v121
	v_add_f32_e32 v121, v76, v121
	v_add_f32_e32 v121, v77, v121
	v_add_f32_e32 v121, v78, v121
	v_add_f32_e32 v121, v79, v121
	v_add_f32_e32 v120, v120, v121
	v_cvt_pk_bf16_f32 v64, v64, v65
	v_cvt_pk_bf16_f32 v65, v66, v67
	v_cvt_pk_bf16_f32 v66, v68, v69
	v_cvt_pk_bf16_f32 v67, v70, v71
	v_cvt_pk_bf16_f32 v68, v72, v73
	v_cvt_pk_bf16_f32 v69, v74, v75
	v_cvt_pk_bf16_f32 v70, v76, v77
	v_cvt_pk_bf16_f32 v71, v78, v79
	s_nop 0
	v_permlane32_swap_b32_e32 v64, v66
	v_permlane32_swap_b32_e32 v65, v67
	v_permlane32_swap_b32_e32 v68, v70
	v_permlane32_swap_b32_e32 v69, v71
	s_waitcnt lgkmcnt(0)
	s_add_i32 s99, s22, 0xffffc000
	s_and_b32 s99, s99, 0x6000
	v_add_u32_e32 v123, s99, v114
	v_add_u32_e32 v140, v123, v118
	v_add_u32_e32 v136, v123, v117
	v_add_u32_e32 v132, v123, v116
	v_add_u32_e32 v123, v123, v115
	ds_read_b128 v[124:127], v123
	ds_read_b128 v[132:135], v132
	ds_read_b128 v[136:139], v136
	ds_read_b128 v[140:143], v140
	s_setprio 1
	s_cmp_lt_u32 s33, 0x100
	s_cbranch_scc1 .Lstg_d0_mid_11
	s_waitcnt vmcnt(3)
	s_barrier

; #define LAS __attribute__((address_space(3)))
; DI int v_rd_base(int lane) { return ((lane & 3) << 3) | (((lane >> 2) & 3) << 6) | (((lane >> 4) & 1) << 5) | (((lane >> 5) & 1) << 8); }
; DI void pv_mma(f32x16* o, const s16x4* vf, bf16x8 pa0, bf16x8 pa1) {
;     ...
; #pragma unroll
;     for (int d0 = 0; d0 < 4; ++d0) {
;         o[d0] = __builtin_amdgcn_mfma_f32_32x32x16_bf16(pa0, ATT_PK(vf[4 * d0], vf[4 * d0 + 1]), o[d0], 0, 0, 0);
;         o[d0] = __builtin_amdgcn_mfma_f32_32x32x16_bf16(pa1, ATT_PK(vf[4 * d0 + 2], vf[4 * d0 + 3]), o[d0], 0, 0, 0); }
;     ...
; }
; template <int DQK, int D0A, int D0B> DI void k_reads(bf16x8* kf, const LAS unsigned char* Ks, int half, int r32, int hi) {
; #pragma unroll
;     for (int d0 = D0A; d0 < D0B; ++d0) kf[d0 - D0A] = *(const LAS bf16x8*)(Ks + half * (32 * DQK * 2) + kswz<DQK>(r32, (d0 * 16 + hi * 8) * 2));
; }
; template <int D0A, int D0B> DI void qk_mma(f32x16& p, const bf16x8* kf, const bf16x8* qr) {
; #pragma unroll
;     for (int d0 = D0A; d0 < D0B; ++d0) {
;         if (d0 == 0) { f32x16 z; _Pragma("unroll") for (int r = 0; r < 16; ++r) z[r] = 0.f; p = __builtin_amdgcn_mfma_f32_32x32x16_bf16(kf[0], qr[0], z, 0, 0, 0); }
;         else p = __builtin_amdgcn_mfma_f32_32x32x16_bf16(kf[d0 - D0A], qr[d0], p, 0, 0, 0); }
; }
; template <int DQK, int MODE, int LDQ, int LDK, int LDV> ...
;     ...
;     const int vbase = (int)(unsigned)(size_t)lds + V_OFF + v_rd_base(lane);
;     ...
;     constexpr int NDA = ND0 > 6 ? 6 : ND0;
.LBB0_1953:
	s_add_i32 s3, s0, -1
	s_lshl_b32 s2, s23, 14
	v_add_u32_e32 v121, s2, v106
	ds_read_b64_tr_b16 v[144:145], v121 offset:0
	ds_read_b64_tr_b16 v[146:147], v121 offset:0x800
	ds_read_b64_tr_b16 v[148:149], v121 offset:0x1000
	ds_read_b64_tr_b16 v[150:151], v121 offset:0x1800
	ds_read_b64_tr_b16 v[152:153], v121 offset:0x200
	ds_read_b64_tr_b16 v[154:155], v121 offset:0xa00
	ds_read_b64_tr_b16 v[156:157], v121 offset:0x1200
	ds_read_b64_tr_b16 v[158:159], v121 offset:0x1a00
	ds_read_b64_tr_b16 v[162:163], v121 offset:0x400
	ds_read_b64_tr_b16 v[164:165], v121 offset:0xc00
	ds_read_b64_tr_b16 v[166:167], v121 offset:0x1400
	ds_read_b64_tr_b16 v[168:169], v121 offset:0x1c00
	ds_read_b64_tr_b16 v[170:171], v121 offset:0x600
	ds_read_b64_tr_b16 v[172:173], v121 offset:0xe00
	ds_read_b64_tr_b16 v[174:175], v121 offset:0x1600
	ds_read_b64_tr_b16 v[176:177], v121 offset:0x1e00
	s_setprio 2
	v_exp_f32_e32 v64, v64
	v_exp_f32_e32 v65, v65
	v_exp_f32_e32 v66, v66
	v_exp_f32_e32 v67, v67
	v_exp_f32_e32 v68, v68
	v_exp_f32_e32 v69, v69
	v_add_f32_e32 v126, v65, v64
	v_exp_f32_e32 v70, v70
	v_add_f32_e32 v126, v66, v126
	v_exp_f32_e32 v71, v71
	v_add_f32_e32 v126, v67, v126
	v_exp_f32_e32 v72, v72
	v_add_f32_e32 v126, v68, v126
	v_exp_f32_e32 v73, v73
	v_add_f32_e32 v126, v69, v126
	v_exp_f32_e32 v74, v74
	v_add_f32_e32 v126, v70, v126
	v_exp_f32_e32 v75, v75
	v_add_f32_e32 v126, v71, v126
	v_exp_f32_e32 v76, v76
	v_add_f32_e32 v126, v72, v126
	v_exp_f32_e32 v77, v77
	v_add_f32_e32 v126, v73, v126
	v_exp_f32_e32 v78, v78
	v_add_f32_e32 v126, v74, v126
	v_exp_f32_e32 v79, v79
	v_add_f32_e32 v126, v75, v126
	v_add_f32_e32 v126, v76, v126
	v_add_f32_e32 v126, v77, v126
	v_add_f32_e32 v126, v78, v126
	v_add_f32_e32 v126, v79, v126
	v_add_f32_e32 v120, v126, v120
	v_cvt_pk_bf16_f32 v64, v64, v65
	v_cvt_pk_bf16_f32 v65, v66, v67
	v_cvt_pk_bf16_f32 v66, v68, v69
	v_cvt_pk_bf16_f32 v67, v70, v71
	v_cvt_pk_bf16_f32 v68, v72, v73
	v_cvt_pk_bf16_f32 v69, v74, v75
	v_cvt_pk_bf16_f32 v70, v76, v77
	v_cvt_pk_bf16_f32 v71, v78, v79
	s_nop 0
	v_permlane32_swap_b32_e32 v64, v66
	v_permlane32_swap_b32_e32 v65, v67
	v_permlane32_swap_b32_e32 v68, v70
	v_permlane32_swap_b32_e32 v69, v71
	s_waitcnt lgkmcnt(0)
	s_add_i32 s99, s22, 0xffffa000
	s_and_b32 s99, s99, 0x6000
	v_add_u32_e32 v196, s99, v114
	v_add_u32_e32 v197, v196, v115
	v_add_u32_e32 v198, v196, v116
	v_add_u32_e32 v199, v196, v117
	v_add_u32_e32 v196, v196, v118
	ds_read_b128 v[122:125], v197 offset:4096
	ds_read_b128 v[132:135], v198 offset:4096
	ds_read_b128 v[136:139], v199 offset:4096
	ds_read_b128 v[140:143], v196 offset:4096
	s_setprio 1
	v_mfma_f32_32x32x16_bf16 v[0:15], v[64:67], v[144:147], v[0:15]
	s_cmp_lt_i32 s3, s47
	s_cselect_b64 s[74:75], -1, 0
	s_cmp_ge_i32 s3, s52
	s_cselect_b64 s[90:91], -1, 0
	s_or_b64 s[74:75], s[74:75], s[90:91]
	s_and_b64 vcc, exec, s[74:75]
	v_mfma_f32_32x32x16_bf16 v[48:63], v[64:67], v[152:155], v[48:63]
	v_mfma_f32_32x32x16_bf16 v[16:31], v[64:67], v[162:165], v[16:31]
	v_mfma_f32_32x32x16_bf16 v[32:47], v[64:67], v[170:173], v[32:47]
	v_mfma_f32_32x32x16_bf16 v[0:15], v[68:71], v[148:151], v[0:15]
	v_mfma_f32_32x32x16_bf16 v[48:63], v[68:71], v[156:159], v[48:63]
	v_mfma_f32_32x32x16_bf16 v[16:31], v[68:71], v[166:169], v[16:31]
	v_mfma_f32_32x32x16_bf16 v[32:47], v[68:71], v[174:177], v[32:47]
	s_waitcnt lgkmcnt(0)
	v_mfma_f32_32x32x16_bf16 v[64:79], v[122:125], v[92:95], 0
	v_mfma_f32_32x32x16_bf16 v[64:79], v[132:135], v[88:91], v[64:79]
	v_mfma_f32_32x32x16_bf16 v[64:79], v[136:139], v[84:87], v[64:79]
	v_mfma_f32_32x32x16_bf16 v[64:79], v[140:143], v[80:83], v[64:79]
	s_setprio 0
	v_add_u32_e32 v122, s7, v119
	s_cbranch_vccnz .LBB0_1955
	v_add_u32_e32 v138, 0x28908, v122
	v_add_u32_e32 v140, 0x28920, v122
	v_add_u32_e32 v142, 0x28928, v122
	v_add_u32_e32 v124, 0x28940, v122
	v_add_u32_e32 v126, 0x28948, v122
	v_add_u32_e32 v132, 0x28960, v122
	v_add_u32_e32 v134, 0x28968, v122
	v_add_u32_e32 v123, 0x28900, v122
	ds_read2_b32 v[124:125], v124 offset1:1
	ds_read2_b32 v[126:127], v126 offset1:1
	ds_read2_b32 v[132:133], v132 offset1:1
	ds_read2_b32 v[134:135], v134 offset1:1
	ds_read2_b32 v[136:137], v123 offset1:1
	ds_read2_b32 v[138:139], v138 offset1:1
	ds_read2_b32 v[140:141], v140 offset1:1
	ds_read2_b32 v[142:143], v142 offset1:1
	s_waitcnt lgkmcnt(0)
	v_pk_add_f32 v[78:79], v[78:79], v[134:135]
	v_pk_add_f32 v[76:77], v[76:77], v[132:133]
	v_pk_add_f32 v[74:75], v[74:75], v[126:127]
	v_pk_add_f32 v[72:73], v[72:73], v[124:125]
	v_pk_add_f32 v[70:71], v[70:71], v[142:143]
	v_pk_add_f32 v[68:69], v[68:69], v[140:141]
	v_pk_add_f32 v[66:67], v[66:67], v[138:139]
	v_pk_add_f32 v[64:65], v[64:65], v[136:137]
